# store acknowledgements no longer awaited before the tile-start barrier of the combined input projection (main and remainder tiles) and the item-loop barrier of the mix phase
# baseline (speedup 1.0000x reference)
.LBB0_117:
	s_waitcnt lgkmcnt(0)
	s_barrier
	s_mov_b64 s[4:5], exec
	v_readlane_b32 s0, v217, 3
	v_readlane_b32 s1, v217, 4
	s_and_b64 s[0:1], s[4:5], s[0:1]
	s_mov_b64 exec, s[0:1]
	s_cbranch_execz .LBB0_131
	s_xor_b64 s[8:9], s[96:97], -1
	v_mov_b32_e32 v2, -1
	s_mov_b64 s[6:7], -1
	s_and_saveexec_b64 s[0:1], s[8:9]
	s_cbranch_execz .LBB0_122
	s_mov_b64 s[8:9], exec
	v_mbcnt_lo_u32_b32 v0, s8, 0
	v_mbcnt_hi_u32_b32 v0, s9, v0
	v_cmp_eq_u32_e32 vcc, 0, v0
	s_and_saveexec_b64 s[6:7], vcc
	s_cbranch_execz .LBB0_121
	s_bcnt1_i32_b64 s8, s[8:9]
	v_mov_b32_e32 v2, s8
	v_readlane_b32 s8, v214, 61
	v_readlane_b32 s9, v214, 62
	s_nop 4
	global_atomic_add v2, v1, v2, s[8:9] sc0

.LBB0_276:
	v_mov_b32_e32 v0, v142
	v_mov_b32_e32 v2, v142
	s_lshl_b32 s2, s17, 8
	v_lshlrev_b32_e32 v5, 7, v2
	v_lshlrev_b32_e32 v4, 6, v2
	v_and_b32_e32 v31, 0x2000, v5
	v_lshlrev_b32_e32 v5, 2, v2
	v_and_b32_e32 v3, 48, v2
	v_and_b32_e32 v30, 0xffffe000, v4
	v_and_b32_e32 v4, 0x3c0, v4
	v_and_b32_e32 v5, 32, v5
	v_bitop3_b32 v32, v4, v5, v3 bitop3:0x36
	v_ashrrev_i32_e32 v3, 31, v2
	v_lshrrev_b32_e32 v3, 26, v3
	v_lshlrev_b32_e32 v33, 4, v2
	v_add_u32_e32 v3, v2, v3
	v_bfe_i32 v2, v2, 27, 1
	v_lshrrev_b32_e32 v2, 22, v2
	v_add_u32_e32 v2, v33, v2
	v_and_b32_e32 v2, 0xfffffc00, v2
	v_sub_u32_e32 v2, v33, v2
	v_lshrrev_b32_e32 v4, 4, v2
	v_bitop3_b32 v4, v4, v2, 32 bitop3:0x6c
	v_ashrrev_i32_e32 v2, 31, v2
	v_ashrrev_i32_e32 v3, 6, v3
	v_lshrrev_b32_e32 v2, 26, v2
	v_lshlrev_b32_e32 v5, 3, v3
	v_add_u32_e32 v2, v4, v2
	v_and_b32_e32 v5, -16, v5
	v_ashrrev_i32_e32 v6, 6, v2
	v_add_u32_e32 v2, v6, v5
	v_mul_i32_i24_e32 v5, 64, v6
	s_ashr_i32 s3, s2, 31
	v_lshlrev_b32_e32 v3, 5, v3
	v_sub_u32_e32 v4, v4, v5
	s_lshl_b32 s40, s18, 7
	s_lshl_b64 s[4:5], s[2:3], 11
	v_and_b32_e32 v3, 32, v3
	v_ashrrev_i16_sdwa v4, v146, sext(v4) dst_sel:DWORD dst_unused:UNUSED_PAD src0_sel:DWORD src1_sel:BYTE_0
	s_add_u32 s10, s24, s4
	v_add_u32_sdwa v4, v3, sext(v4) dst_sel:DWORD dst_unused:UNUSED_PAD src0_sel:DWORD src1_sel:WORD_0
	v_ashrrev_i32_e32 v3, 31, v2
	s_addc_u32 s11, s25, s5
	v_lshlrev_b64 v[2:3], 11, v[2:3]
	v_ashrrev_i32_e32 v5, 31, v4
	v_add_u32_e32 v78, 0, v33
	v_add_u32_e32 v34, 0x2000, v33
	v_lshl_add_u64 v[6:7], s[10:11], 0, v[2:3]
	v_lshlrev_b64 v[4:5], 1, v[4:5]
	v_readfirstlane_b32 s19, v78
	v_ashrrev_i32_e32 v8, 31, v34
	v_add_u32_e32 v14, 0x2000, v78
	v_add_u32_e32 v35, 0x4000, v33
	v_lshl_add_u64 v[6:7], v[6:7], 0, v[4:5]
	s_mov_b32 m0, s19
	v_lshrrev_b32_e32 v8, 22, v8
	v_readfirstlane_b32 s19, v14
	v_ashrrev_i32_e32 v14, 31, v35
	v_add_u32_e32 v20, 0x4000, v78
	v_add_u32_e32 v36, 0x6000, v33
	s_waitcnt lgkmcnt(0)
	s_barrier
	global_load_lds_dwordx4 v[6:7], off
	v_add_u32_e32 v8, v34, v8
	s_mov_b32 m0, s19
	v_lshrrev_b32_e32 v14, 22, v14
	v_readfirstlane_b32 s19, v20
	v_ashrrev_i32_e32 v20, 31, v36
	v_ashrrev_i32_e32 v9, 10, v8
	v_add_u32_e32 v14, v35, v14
	v_lshrrev_b32_e32 v20, 22, v20
	v_mul_i32_i24_e32 v8, 0x400, v9
	v_ashrrev_i32_e32 v15, 10, v14
	v_add_u32_e32 v20, v36, v20
	v_sub_u32_e32 v8, v34, v8
	v_mul_i32_i24_e32 v14, 0x400, v15
	v_ashrrev_i32_e32 v21, 10, v20
	v_lshrrev_b32_e32 v10, 4, v8
	v_sub_u32_e32 v14, v35, v14
	v_mul_i32_i24_e32 v20, 0x400, v21
	v_bitop3_b32 v10, v10, v8, 32 bitop3:0x6c
	v_lshrrev_b32_e32 v16, 4, v14
	v_sub_u32_e32 v20, v36, v20
	v_ashrrev_i32_e32 v11, 31, v10
	v_bitop3_b32 v16, v16, v14, 32 bitop3:0x6c
	v_lshrrev_b32_e32 v22, 4, v20
	v_lshrrev_b32_e32 v11, 26, v11
	v_ashrrev_i32_e32 v17, 31, v16
	v_bitop3_b32 v22, v22, v20, 32 bitop3:0x6c
	v_add_u32_e32 v11, v10, v11
	v_lshrrev_b32_e32 v17, 26, v17
	v_ashrrev_i32_e32 v23, 31, v22
	v_lshlrev_b32_e32 v8, 3, v9
	v_ashrrev_i32_e32 v12, 6, v11
	v_and_b32_e32 v11, 0xc0, v11
	v_add_u32_e32 v17, v16, v17
	v_lshrrev_b32_e32 v23, 26, v23
	v_and_b32_e32 v8, -16, v8
	v_lshlrev_b32_e32 v9, 5, v9
	v_sub_u32_e32 v10, v10, v11
	v_lshlrev_b32_e32 v14, 3, v15
	v_ashrrev_i32_e32 v18, 6, v17
	v_and_b32_e32 v17, 0xc0, v17
	v_add_u32_e32 v23, v22, v23
	v_add_u32_e32 v8, v12, v8
	v_and_b32_e32 v9, 32, v9
	v_ashrrev_i16_sdwa v10, v146, sext(v10) dst_sel:DWORD dst_unused:UNUSED_PAD src0_sel:DWORD src1_sel:BYTE_0
	v_and_b32_e32 v14, -16, v14
	v_lshlrev_b32_e32 v15, 5, v15
	v_sub_u32_e32 v16, v16, v17
	v_lshlrev_b32_e32 v20, 3, v21
	v_ashrrev_i32_e32 v24, 6, v23
	v_and_b32_e32 v23, 0xc0, v23
	v_add_u32_sdwa v10, v9, sext(v10) dst_sel:DWORD dst_unused:UNUSED_PAD src0_sel:DWORD src1_sel:WORD_0
	v_ashrrev_i32_e32 v9, 31, v8
	v_add_u32_e32 v14, v18, v14
	v_and_b32_e32 v15, 32, v15
	v_ashrrev_i16_sdwa v16, v146, sext(v16) dst_sel:DWORD dst_unused:UNUSED_PAD src0_sel:DWORD src1_sel:BYTE_0
	v_and_b32_e32 v20, -16, v20
	v_lshlrev_b32_e32 v21, 5, v21
	v_sub_u32_e32 v22, v22, v23
	s_ashr_i32 s41, s40, 31
	v_lshlrev_b64 v[8:9], 11, v[8:9]
	v_ashrrev_i32_e32 v11, 31, v10
	v_add_u32_sdwa v16, v15, sext(v16) dst_sel:DWORD dst_unused:UNUSED_PAD src0_sel:DWORD src1_sel:WORD_0
	v_ashrrev_i32_e32 v15, 31, v14
	v_add_u32_e32 v20, v24, v20
	v_and_b32_e32 v21, 32, v21
	v_ashrrev_i16_sdwa v22, v146, sext(v22) dst_sel:DWORD dst_unused:UNUSED_PAD src0_sel:DWORD src1_sel:BYTE_0
	s_lshl_b64 s[6:7], s[40:41], 11
	v_lshl_add_u64 v[12:13], s[10:11], 0, v[8:9]
	v_lshlrev_b64 v[10:11], 1, v[10:11]
	v_lshlrev_b64 v[14:15], 11, v[14:15]
	v_ashrrev_i32_e32 v17, 31, v16
	v_add_u32_sdwa v22, v21, sext(v22) dst_sel:DWORD dst_unused:UNUSED_PAD src0_sel:DWORD src1_sel:WORD_0
	v_ashrrev_i32_e32 v21, 31, v20
	s_add_u32 s8, s14, s6
	v_lshl_add_u64 v[12:13], v[12:13], 0, v[10:11]
	v_lshl_add_u64 v[18:19], s[10:11], 0, v[14:15]
	v_lshlrev_b64 v[16:17], 1, v[16:17]
	v_lshlrev_b64 v[20:21], 11, v[20:21]
	v_ashrrev_i32_e32 v23, 31, v22
	v_add_u32_e32 v26, 0x6000, v78
	s_addc_u32 s9, s15, s7
	global_load_lds_dwordx4 v[12:13], off
	v_lshl_add_u64 v[18:19], v[18:19], 0, v[16:17]
	s_mov_b32 m0, s19
	v_lshl_add_u64 v[24:25], s[10:11], 0, v[20:21]
	v_lshlrev_b64 v[22:23], 1, v[22:23]
	v_readfirstlane_b32 s10, v26
	v_add_u32_e32 v28, 0x8000, v78
	global_load_lds_dwordx4 v[18:19], off
	v_lshl_add_u64 v[24:25], v[24:25], 0, v[22:23]
	s_mov_b32 m0, s10
	v_lshl_add_u64 v[26:27], s[8:9], 0, v[2:3]
	v_readfirstlane_b32 s10, v28
	v_add_u32_e32 v37, 0xa000, v78
	global_load_lds_dwordx4 v[24:25], off
	v_lshl_add_u64 v[26:27], v[26:27], 0, v[4:5]
	s_mov_b32 m0, s10
	v_lshl_add_u64 v[28:29], s[8:9], 0, v[8:9]
	v_readfirstlane_b32 s8, v37
	v_add_u32_e32 v37, 0xc000, v78
	global_load_lds_dwordx4 v[26:27], off
	v_lshl_add_u64 v[28:29], v[28:29], 0, v[10:11]
	s_mov_b32 m0, s8
	v_readfirstlane_b32 s8, v37
	global_load_lds_dwordx4 v[28:29], off
	v_lshl_add_u64 v[6:7], v[6:7], 0, s[30:31]
	s_mov_b32 m0, s8
	s_mov_b32 s3, 2
	global_load_lds_dwordx4 v[6:7], off
	v_lshl_add_u64 v[6:7], v[12:13], 0, s[30:31]
	v_add_u32_e32 v12, 0xe000, v78
	v_add3_u32 v80, v30, 0, v32
	v_readfirstlane_b32 s8, v12
	s_mov_b32 m0, s8
	s_add_i32 s8, 0, 0xc000
	v_add_u32_e32 v12, s8, v35
	global_load_lds_dwordx4 v[6:7], off
	v_readfirstlane_b32 s9, v12
	v_add_u32_e32 v12, s8, v36
	v_lshl_add_u64 v[6:7], v[18:19], 0, s[30:31]
	s_mov_b32 m0, s9
	v_readfirstlane_b32 s8, v12
	v_add_u32_e32 v12, s54, v33
	global_load_lds_dwordx4 v[6:7], off
	v_lshl_add_u64 v[6:7], v[24:25], 0, s[30:31]
	s_mov_b32 m0, s8
	v_readfirstlane_b32 s8, v12
	v_add_u32_e32 v12, s54, v34
	global_load_lds_dwordx4 v[6:7], off
	v_lshl_add_u64 v[6:7], v[26:27], 0, s[30:31]
	s_mov_b32 m0, s8
	v_readfirstlane_b32 s8, v12
	global_load_lds_dwordx4 v[6:7], off
	v_lshl_add_u64 v[6:7], v[28:29], 0, s[30:31]
	s_mov_b32 m0, s8
	s_add_i32 s8, 0, 0x8000
	global_load_lds_dwordx4 v[6:7], off
	v_lshl_add_u64 v[6:7], s[6:7], 0, v[8:9]
	v_lshl_add_u64 v[6:7], v[6:7], 0, v[10:11]
	v_lshl_add_u64 v[66:67], s[0:1], 0, v[6:7]
	v_lshl_add_u64 v[6:7], s[6:7], 0, v[2:3]
	v_lshl_add_u64 v[6:7], v[6:7], 0, v[4:5]
	v_lshl_add_u64 v[68:69], s[0:1], 0, v[6:7]
	v_lshl_add_u64 v[6:7], s[4:5], 0, v[20:21]
	v_lshl_add_u64 v[6:7], v[6:7], 0, v[22:23]
	v_lshl_add_u64 v[70:71], s[90:91], 0, v[6:7]
	v_lshl_add_u64 v[6:7], s[4:5], 0, v[14:15]
	v_lshl_add_u64 v[6:7], v[6:7], 0, v[16:17]
	v_lshl_add_u64 v[2:3], s[4:5], 0, v[2:3]
	v_lshl_add_u64 v[72:73], s[90:91], 0, v[6:7]
	v_lshl_add_u64 v[6:7], s[4:5], 0, v[8:9]
	v_lshl_add_u64 v[2:3], v[2:3], 0, v[4:5]
	v_lshl_add_u64 v[6:7], v[6:7], 0, v[10:11]
	v_lshl_add_u64 v[76:77], s[90:91], 0, v[2:3]
	v_mov_b32_e32 v2, 0
	v_add3_u32 v79, v31, s8, v32
	v_lshl_add_u64 v[74:75], s[90:91], 0, v[6:7]
	s_mov_b32 s6, 0
	s_mov_b64 s[4:5], 0
	v_mov_b32_e32 v3, v2
	v_mov_b32_e32 v4, v2
	v_mov_b32_e32 v5, v2
	v_mov_b32_e32 v6, v2
	v_mov_b32_e32 v7, v2
	v_mov_b32_e32 v8, v2
	v_mov_b32_e32 v9, v2
	v_mov_b32_e32 v10, v2
	v_mov_b32_e32 v11, v2
	v_mov_b32_e32 v12, v2
	v_mov_b32_e32 v13, v2
	v_mov_b32_e32 v14, v2
	v_mov_b32_e32 v15, v2
	v_mov_b32_e32 v16, v2
	v_mov_b32_e32 v17, v2
	v_mov_b32_e32 v18, v2
	v_mov_b32_e32 v19, v2
	v_mov_b32_e32 v20, v2
	v_mov_b32_e32 v21, v2
	v_mov_b32_e32 v22, v2
	v_mov_b32_e32 v23, v2
	v_mov_b32_e32 v24, v2
	v_mov_b32_e32 v25, v2
	v_mov_b32_e32 v26, v2
	v_mov_b32_e32 v27, v2
	v_mov_b32_e32 v28, v2
	v_mov_b32_e32 v29, v2
	v_mov_b32_e32 v30, v2
	v_mov_b32_e32 v31, v2
	v_mov_b32_e32 v32, v2
	v_mov_b32_e32 v33, v2
	v_mov_b32_e32 v34, v2
	v_mov_b32_e32 v35, v2
	v_mov_b32_e32 v36, v2
	v_mov_b32_e32 v37, v2
	v_mov_b32_e32 v38, v2
	v_mov_b32_e32 v39, v2
	v_mov_b32_e32 v40, v2
	v_mov_b32_e32 v41, v2
	v_mov_b32_e32 v42, v2
	v_mov_b32_e32 v43, v2
	v_mov_b32_e32 v44, v2
	v_mov_b32_e32 v45, v2
	v_mov_b32_e32 v46, v2
	v_mov_b32_e32 v47, v2
	v_mov_b32_e32 v48, v2
	v_mov_b32_e32 v49, v2
	v_mov_b32_e32 v50, v2
	v_mov_b32_e32 v51, v2
	v_mov_b32_e32 v52, v2
	v_mov_b32_e32 v53, v2
	v_mov_b32_e32 v54, v2
	v_mov_b32_e32 v55, v2
	v_mov_b32_e32 v56, v2
	v_mov_b32_e32 v57, v2
	v_mov_b32_e32 v58, v2
	v_mov_b32_e32 v59, v2
	v_mov_b32_e32 v60, v2
	v_mov_b32_e32 v61, v2
	v_mov_b32_e32 v62, v2
	v_mov_b32_e32 v63, v2
	v_mov_b32_e32 v64, v2
	v_mov_b32_e32 v65, v2

.LBB0_337:
	v_mov_b32_e32 v18, v142
	v_mov_b32_e32 v0, v142
	s_lshl_b32 s8, s18, 8
	v_and_b32_e32 v2, 15, v0
	v_lshlrev_b32_e32 v4, 2, v0
	v_and_b32_e32 v3, 48, v0
	v_lshlrev_b32_e32 v2, 6, v2
	v_and_b32_e32 v4, 32, v4
	v_bitop3_b32 v11, v2, v4, v3 bitop3:0x36
	v_lshlrev_b32_e32 v2, 6, v0
	v_and_b32_e32 v2, 0x3c0, v2
	v_bitop3_b32 v14, v2, v4, v3 bitop3:0x36
	v_ashrrev_i32_e32 v2, 31, v0
	v_lshrrev_b32_e32 v2, 26, v2
	v_lshlrev_b32_e32 v12, 4, v0
	v_lshlrev_b32_e32 v5, 7, v0
	v_add_u32_e32 v2, v0, v2
	v_bfe_i32 v0, v0, 27, 1
	v_lshrrev_b32_e32 v0, 22, v0
	v_add_u32_e32 v0, v12, v0
	v_and_b32_e32 v0, 0xfffffc00, v0
	v_sub_u32_e32 v0, v12, v0
	v_ashrrev_i32_e32 v3, 6, v2
	v_lshrrev_b32_e32 v2, 4, v0
	s_and_b32 s0, s16, 0xc0
	v_bitop3_b32 v4, v2, v0, 32 bitop3:0x6c
	v_ashrrev_i32_e32 v0, 31, v0
	s_or_b32 s0, s8, s0
	v_lshrrev_b32_e32 v0, 26, v0
	s_ashr_i32 s1, s0, 31
	v_lshlrev_b32_e32 v2, 3, v3
	v_add_u32_e32 v0, v4, v0
	s_lshl_b32 s2, s19, 7
	s_lshl_b64 s[4:5], s[0:1], 11
	v_and_b32_e32 v2, -16, v2
	v_ashrrev_i32_e32 v0, 6, v0
	s_add_u32 s6, s24, s4
	v_add_u32_e32 v2, v0, v2
	v_mul_i32_i24_e32 v0, 64, v0
	s_addc_u32 s7, s25, s5
	s_ashr_i32 s3, s2, 31
	v_lshlrev_b32_e32 v3, 5, v3
	v_sub_u32_e32 v0, v4, v0
	s_lshl_b64 s[4:5], s[2:3], 11
	v_and_b32_e32 v3, 32, v3
	v_ashrrev_i16_sdwa v0, v146, sext(v0) dst_sel:DWORD dst_unused:UNUSED_PAD src0_sel:DWORD src1_sel:BYTE_0
	s_add_u32 s4, s14, s4
	v_add_u32_sdwa v4, v3, sext(v0) dst_sel:DWORD dst_unused:UNUSED_PAD src0_sel:DWORD src1_sel:WORD_0
	v_ashrrev_i32_e32 v3, 31, v2
	s_addc_u32 s5, s15, s5
	v_and_b32_e32 v13, 0x2000, v5
	v_lshlrev_b64 v[6:7], 11, v[2:3]
	v_ashrrev_i32_e32 v5, 31, v4
	v_lshl_add_u64 v[2:3], s[6:7], 0, v[6:7]
	v_lshlrev_b64 v[4:5], 1, v[4:5]
	v_add_u32_e32 v0, 0, v12
	v_lshl_add_u64 v[6:7], s[4:5], 0, v[6:7]
	v_lshl_add_u64 v[2:3], v[2:3], 0, v[4:5]
	v_lshl_add_u64 v[4:5], v[6:7], 0, v[4:5]
	v_add_u32_e32 v6, 0x8000, v0
	v_add_u32_e32 v15, 0x2000, v12
	v_readfirstlane_b32 s6, v6
	v_ashrrev_i32_e32 v6, 31, v15
	v_lshrrev_b32_e32 v6, 22, v6
	v_add_u32_e32 v6, v15, v6
	v_ashrrev_i32_e32 v7, 10, v6
	v_mul_i32_i24_e32 v6, 0x400, v7
	v_sub_u32_e32 v6, v15, v6
	v_lshrrev_b32_e32 v8, 4, v6
	v_bitop3_b32 v8, v8, v6, 32 bitop3:0x6c
	v_ashrrev_i32_e32 v9, 31, v8
	v_lshrrev_b32_e32 v9, 26, v9
	v_add_u32_e32 v9, v8, v9
	v_lshlrev_b32_e32 v6, 3, v7
	v_ashrrev_i32_e32 v16, 6, v9
	v_and_b32_e32 v9, 0xc0, v9
	v_and_b32_e32 v6, -16, v6
	v_lshlrev_b32_e32 v7, 5, v7
	v_sub_u32_e32 v8, v8, v9
	v_add_u32_e32 v6, v16, v6
	v_and_b32_e32 v7, 32, v7
	v_ashrrev_i16_sdwa v8, v146, sext(v8) dst_sel:DWORD dst_unused:UNUSED_PAD src0_sel:DWORD src1_sel:BYTE_0
	v_add_u32_sdwa v8, v7, sext(v8) dst_sel:DWORD dst_unused:UNUSED_PAD src0_sel:DWORD src1_sel:WORD_0
	v_ashrrev_i32_e32 v7, 31, v6
	v_lshlrev_b64 v[6:7], 11, v[6:7]
	v_readfirstlane_b32 s1, v0
	v_lshl_add_u64 v[6:7], s[4:5], 0, v[6:7]
	v_ashrrev_i32_e32 v9, 31, v8
	s_mov_b32 m0, s1
	v_lshl_add_u64 v[6:7], v[8:9], 1, v[6:7]
	v_add_u32_e32 v8, 0xa000, v0
	s_waitcnt lgkmcnt(0)
	s_barrier
	global_load_lds_dwordx4 v[2:3], off
	s_mov_b32 m0, s6
	v_readfirstlane_b32 s4, v8
	v_add_u32_e32 v0, 0xc000, v0
	global_load_lds_dwordx4 v[4:5], off
	s_mov_b32 m0, s4
	v_readfirstlane_b32 s7, v0
	v_add_u32_e32 v0, s54, v12
	global_load_lds_dwordx4 v[6:7], off
	v_lshl_add_u64 v[8:9], v[2:3], 0, s[30:31]
	s_mov_b32 m0, s7
	v_readfirstlane_b32 s5, v0
	v_add_u32_e32 v0, s54, v15
	global_load_lds_dwordx4 v[8:9], off
	v_lshl_add_u64 v[8:9], v[4:5], 0, s[30:31]
	s_mov_b32 m0, s5
	v_readfirstlane_b32 s9, v0
	global_load_lds_dwordx4 v[8:9], off
	v_lshl_add_u64 v[8:9], v[6:7], 0, s[30:31]
	s_mov_b32 m0, s9
	v_and_b32_e32 v10, 0xfffff800, v12
	global_load_lds_dwordx4 v[8:9], off
	s_waitcnt vmcnt(3)
	s_add_i32 s10, 0, 0x8000
	v_bfe_u32 v40, v18, 6, 1
	v_add3_u32 v9, v10, 0, v11
	v_add3_u32 v8, v13, s10, v14
	s_barrier
	s_add_i32 s10, 0, 0x18000
	v_add_u32_e32 v0, s10, v12
	s_mov_b32 s20, s89
	s_mov_b64 s[38:39], 0x100
	v_readfirstlane_b32 s11, v0
	v_add_u32_e32 v0, s20, v12
	v_lshl_add_u64 v[10:11], v[2:3], 0, s[38:39]
	s_mov_b32 m0, s11
	v_readfirstlane_b32 s10, v0
	global_load_lds_dwordx4 v[10:11], off
	v_lshl_add_u64 v[10:11], v[4:5], 0, s[38:39]
	s_mov_b32 m0, s10
	v_add_u32_e32 v0, s20, v15
	global_load_lds_dwordx4 v[10:11], off
	v_lshl_add_u64 v[10:11], v[6:7], 0, s[38:39]
	v_readfirstlane_b32 s38, v0
	s_mov_b32 m0, s38
	s_nop 0
	global_load_lds_dwordx4 v[10:11], off
	ds_read_b128 v[10:13], v9 offset:0
	ds_read_b128 v[14:17], v8 offset:0
	ds_read_b128 v[20:23], v8 offset:2048
	ds_read_b128 v[24:27], v8 offset:4096
	ds_read_b128 v[28:31], v8 offset:6144
	ds_read_b128 v[32:35], v9 offset:1024
	ds_read_b128 v[36:39], v8 offset:1024
	ds_read_b128 v[42:45], v8 offset:3072
	ds_read_b128 v[46:49], v8 offset:5120
	ds_read_b128 v[50:53], v8 offset:7168
	s_waitcnt lgkmcnt(5)
	s_nop 0
	v_mfma_f32_16x16x32_bf16 v[14:17], v[14:17], v[10:13], 0
	v_mfma_f32_16x16x32_bf16 v[20:23], v[20:23], v[10:13], 0
	v_mfma_f32_16x16x32_bf16 v[24:27], v[24:27], v[10:13], 0
	v_mfma_f32_16x16x32_bf16 v[10:13], v[28:31], v[10:13], 0
	s_waitcnt lgkmcnt(0)
	v_mfma_f32_16x16x32_bf16 v[14:17], v[36:39], v[32:35], v[14:17]
	v_mfma_f32_16x16x32_bf16 v[20:23], v[42:45], v[32:35], v[20:23]
	v_mfma_f32_16x16x32_bf16 v[24:27], v[46:49], v[32:35], v[24:27]
	v_mfma_f32_16x16x32_bf16 v[28:31], v[50:53], v[32:35], v[10:13]
	s_waitcnt vmcnt(3)
	s_barrier
	s_mov_b64 s[40:41], 0x180
	s_mov_b32 m0, s1
	s_nop 0
	v_lshl_add_u64 v[10:11], v[2:3], 0, s[40:41]
	global_load_lds_dwordx4 v[10:11], off
	v_lshl_add_u64 v[10:11], v[4:5], 0, s[40:41]
	s_mov_b32 m0, s6
	v_add_u32_e32 v0, 0xc000, v8
	global_load_lds_dwordx4 v[10:11], off
	v_lshl_add_u64 v[10:11], v[6:7], 0, s[40:41]
	s_mov_b32 m0, s4
	s_nop 0
	global_load_lds_dwordx4 v[10:11], off
	v_add_u32_e32 v10, 0xc000, v9
	ds_read_b128 v[32:35], v10 offset:0
	ds_read_b128 v[36:39], v0 offset:0
	ds_read_b128 v[42:45], v0 offset:2048
	ds_read_b128 v[46:49], v0 offset:4096
	ds_read_b128 v[50:53], v0 offset:6144
	ds_read_b128 v[54:57], v10 offset:1024
	ds_read_b128 v[58:61], v0 offset:1024
	ds_read_b128 v[62:65], v0 offset:3072
	ds_read_b128 v[66:69], v0 offset:5120
	ds_read_b128 v[70:73], v0 offset:7168
	s_waitcnt lgkmcnt(5)
	s_nop 0
	v_mfma_f32_16x16x32_bf16 v[12:15], v[36:39], v[32:35], v[14:17]
	v_mfma_f32_16x16x32_bf16 v[20:23], v[42:45], v[32:35], v[20:23]
	v_mfma_f32_16x16x32_bf16 v[24:27], v[46:49], v[32:35], v[24:27]
	v_mfma_f32_16x16x32_bf16 v[28:31], v[50:53], v[32:35], v[28:31]
	s_waitcnt lgkmcnt(0)
	v_mfma_f32_16x16x32_bf16 v[14:17], v[58:61], v[54:57], v[12:15]
	v_mfma_f32_16x16x32_bf16 v[20:23], v[62:65], v[54:57], v[20:23]
	v_mfma_f32_16x16x32_bf16 v[24:27], v[66:69], v[54:57], v[24:27]
	v_mfma_f32_16x16x32_bf16 v[28:31], v[70:73], v[54:57], v[28:31]
	s_waitcnt vmcnt(3)
	s_barrier
	s_mov_b64 s[40:41], 0x200
	s_mov_b32 m0, s7
	v_lshl_add_u64 v[12:13], v[2:3], 0, s[40:41]
	global_load_lds_dwordx4 v[12:13], off
	v_lshl_add_u64 v[12:13], v[4:5], 0, s[40:41]
	s_mov_b32 m0, s5
	v_add_u32_e32 v11, 0x18000, v8
	global_load_lds_dwordx4 v[12:13], off
	v_lshl_add_u64 v[12:13], v[6:7], 0, s[40:41]
	s_mov_b32 m0, s9
	s_nop 0
	global_load_lds_dwordx4 v[12:13], off
	v_add_u32_e32 v12, 0x18000, v9
	ds_read_b128 v[32:35], v12 offset:0
	ds_read_b128 v[36:39], v11 offset:0
	ds_read_b128 v[42:45], v11 offset:2048
	ds_read_b128 v[46:49], v11 offset:4096
	ds_read_b128 v[50:53], v11 offset:6144
	ds_read_b128 v[54:57], v12 offset:1024
	ds_read_b128 v[58:61], v11 offset:1024
	ds_read_b128 v[62:65], v11 offset:3072
	ds_read_b128 v[66:69], v11 offset:5120
	ds_read_b128 v[70:73], v11 offset:7168
	s_waitcnt lgkmcnt(5)
	s_nop 0
	v_mfma_f32_16x16x32_bf16 v[14:17], v[36:39], v[32:35], v[14:17]
	v_mfma_f32_16x16x32_bf16 v[20:23], v[42:45], v[32:35], v[20:23]
	v_mfma_f32_16x16x32_bf16 v[24:27], v[46:49], v[32:35], v[24:27]
	v_mfma_f32_16x16x32_bf16 v[28:31], v[50:53], v[32:35], v[28:31]
	s_waitcnt lgkmcnt(0)
	v_mfma_f32_16x16x32_bf16 v[14:17], v[58:61], v[54:57], v[14:17]
	v_mfma_f32_16x16x32_bf16 v[20:23], v[62:65], v[54:57], v[20:23]
	v_mfma_f32_16x16x32_bf16 v[24:27], v[66:69], v[54:57], v[24:27]
	v_mfma_f32_16x16x32_bf16 v[28:31], v[70:73], v[54:57], v[28:31]
	s_waitcnt vmcnt(3)
	s_barrier
	s_mov_b64 s[40:41], 0x280
	s_mov_b32 m0, s11
	v_lshl_add_u64 v[32:33], v[2:3], 0, s[40:41]
	global_load_lds_dwordx4 v[32:33], off
	v_lshl_add_u64 v[32:33], v[4:5], 0, s[40:41]
	s_mov_b32 m0, s10
	s_nop 0
	global_load_lds_dwordx4 v[32:33], off
	v_lshl_add_u64 v[32:33], v[6:7], 0, s[40:41]
	s_mov_b32 m0, s38
	s_nop 0
	global_load_lds_dwordx4 v[32:33], off
	ds_read_b128 v[32:35], v9 offset:0
	ds_read_b128 v[36:39], v8 offset:0
	ds_read_b128 v[42:45], v8 offset:2048
	ds_read_b128 v[46:49], v8 offset:4096
	ds_read_b128 v[50:53], v8 offset:6144
	ds_read_b128 v[54:57], v9 offset:1024
	ds_read_b128 v[58:61], v8 offset:1024
	ds_read_b128 v[62:65], v8 offset:3072
	ds_read_b128 v[66:69], v8 offset:5120
	ds_read_b128 v[70:73], v8 offset:7168
	s_waitcnt lgkmcnt(5)
	s_nop 0
	v_mfma_f32_16x16x32_bf16 v[14:17], v[36:39], v[32:35], v[14:17]
	v_mfma_f32_16x16x32_bf16 v[20:23], v[42:45], v[32:35], v[20:23]
	v_mfma_f32_16x16x32_bf16 v[24:27], v[46:49], v[32:35], v[24:27]
	v_mfma_f32_16x16x32_bf16 v[28:31], v[50:53], v[32:35], v[28:31]
	s_waitcnt lgkmcnt(0)
	v_mfma_f32_16x16x32_bf16 v[14:17], v[58:61], v[54:57], v[14:17]
	v_mfma_f32_16x16x32_bf16 v[20:23], v[62:65], v[54:57], v[20:23]
	v_mfma_f32_16x16x32_bf16 v[24:27], v[66:69], v[54:57], v[24:27]
	v_mfma_f32_16x16x32_bf16 v[28:31], v[70:73], v[54:57], v[28:31]
	s_waitcnt vmcnt(3)
	s_barrier
	s_mov_b64 s[40:41], 0x300
	s_mov_b32 m0, s1
	v_lshl_add_u64 v[32:33], v[2:3], 0, s[40:41]
	global_load_lds_dwordx4 v[32:33], off
	v_lshl_add_u64 v[32:33], v[4:5], 0, s[40:41]
	s_mov_b32 m0, s6
	s_nop 0
	global_load_lds_dwordx4 v[32:33], off
	v_lshl_add_u64 v[32:33], v[6:7], 0, s[40:41]
	s_mov_b32 m0, s4
	s_nop 0
	global_load_lds_dwordx4 v[32:33], off
	ds_read_b128 v[32:35], v10 offset:0
	ds_read_b128 v[36:39], v0 offset:0
	ds_read_b128 v[42:45], v0 offset:2048
	ds_read_b128 v[46:49], v0 offset:4096
	ds_read_b128 v[50:53], v0 offset:6144
	ds_read_b128 v[54:57], v10 offset:1024
	ds_read_b128 v[58:61], v0 offset:1024
	ds_read_b128 v[62:65], v0 offset:3072
	ds_read_b128 v[66:69], v0 offset:5120
	ds_read_b128 v[70:73], v0 offset:7168
	s_waitcnt lgkmcnt(5)
	s_nop 0
	v_mfma_f32_16x16x32_bf16 v[14:17], v[36:39], v[32:35], v[14:17]
	v_mfma_f32_16x16x32_bf16 v[20:23], v[42:45], v[32:35], v[20:23]
	v_mfma_f32_16x16x32_bf16 v[24:27], v[46:49], v[32:35], v[24:27]
	v_mfma_f32_16x16x32_bf16 v[28:31], v[50:53], v[32:35], v[28:31]
	s_waitcnt lgkmcnt(0)
	v_mfma_f32_16x16x32_bf16 v[14:17], v[58:61], v[54:57], v[14:17]
	v_mfma_f32_16x16x32_bf16 v[20:23], v[62:65], v[54:57], v[20:23]
	v_mfma_f32_16x16x32_bf16 v[24:27], v[66:69], v[54:57], v[24:27]
	v_mfma_f32_16x16x32_bf16 v[28:31], v[70:73], v[54:57], v[28:31]
	s_waitcnt vmcnt(3)
	s_barrier
	s_mov_b64 s[40:41], 0x380
	s_mov_b32 m0, s7
	v_lshl_add_u64 v[32:33], v[2:3], 0, s[40:41]
	global_load_lds_dwordx4 v[32:33], off
	v_lshl_add_u64 v[32:33], v[4:5], 0, s[40:41]
	s_mov_b32 m0, s5
	s_nop 0
	global_load_lds_dwordx4 v[32:33], off
	v_lshl_add_u64 v[32:33], v[6:7], 0, s[40:41]
	s_mov_b32 m0, s9
	s_nop 0
	global_load_lds_dwordx4 v[32:33], off
	ds_read_b128 v[32:35], v12 offset:0
	ds_read_b128 v[36:39], v11 offset:0
	ds_read_b128 v[42:45], v11 offset:2048
	ds_read_b128 v[46:49], v11 offset:4096
	ds_read_b128 v[50:53], v11 offset:6144
	ds_read_b128 v[54:57], v12 offset:1024
	ds_read_b128 v[58:61], v11 offset:1024
	ds_read_b128 v[62:65], v11 offset:3072
	ds_read_b128 v[66:69], v11 offset:5120
	ds_read_b128 v[70:73], v11 offset:7168
	s_waitcnt lgkmcnt(5)
	s_nop 0
	v_mfma_f32_16x16x32_bf16 v[14:17], v[36:39], v[32:35], v[14:17]
	v_mfma_f32_16x16x32_bf16 v[20:23], v[42:45], v[32:35], v[20:23]
	v_mfma_f32_16x16x32_bf16 v[24:27], v[46:49], v[32:35], v[24:27]
	v_mfma_f32_16x16x32_bf16 v[28:31], v[50:53], v[32:35], v[28:31]
	s_waitcnt lgkmcnt(0)
	v_mfma_f32_16x16x32_bf16 v[14:17], v[58:61], v[54:57], v[14:17]
	v_mfma_f32_16x16x32_bf16 v[20:23], v[62:65], v[54:57], v[20:23]
	v_mfma_f32_16x16x32_bf16 v[24:27], v[66:69], v[54:57], v[24:27]
	v_mfma_f32_16x16x32_bf16 v[28:31], v[70:73], v[54:57], v[28:31]
	s_waitcnt vmcnt(3)
	s_barrier
	s_mov_b64 s[40:41], 0x400
	s_mov_b32 m0, s11
	v_lshl_add_u64 v[32:33], v[2:3], 0, s[40:41]
	global_load_lds_dwordx4 v[32:33], off
	v_lshl_add_u64 v[32:33], v[4:5], 0, s[40:41]
	s_mov_b32 m0, s10
	s_nop 0
	global_load_lds_dwordx4 v[32:33], off
	v_lshl_add_u64 v[32:33], v[6:7], 0, s[40:41]
	s_mov_b32 m0, s38
	s_nop 0
	global_load_lds_dwordx4 v[32:33], off
	ds_read_b128 v[32:35], v9 offset:0
	ds_read_b128 v[36:39], v8 offset:0
	ds_read_b128 v[42:45], v8 offset:2048
	ds_read_b128 v[46:49], v8 offset:4096
	ds_read_b128 v[50:53], v8 offset:6144
	ds_read_b128 v[54:57], v9 offset:1024
	ds_read_b128 v[58:61], v8 offset:1024
	ds_read_b128 v[62:65], v8 offset:3072
	ds_read_b128 v[66:69], v8 offset:5120
	ds_read_b128 v[70:73], v8 offset:7168
	s_waitcnt lgkmcnt(5)
	s_nop 0
	v_mfma_f32_16x16x32_bf16 v[14:17], v[36:39], v[32:35], v[14:17]
	v_mfma_f32_16x16x32_bf16 v[20:23], v[42:45], v[32:35], v[20:23]
	v_mfma_f32_16x16x32_bf16 v[24:27], v[46:49], v[32:35], v[24:27]
	v_mfma_f32_16x16x32_bf16 v[28:31], v[50:53], v[32:35], v[28:31]
	s_waitcnt lgkmcnt(0)
	v_mfma_f32_16x16x32_bf16 v[14:17], v[58:61], v[54:57], v[14:17]
	v_mfma_f32_16x16x32_bf16 v[20:23], v[62:65], v[54:57], v[20:23]
	v_mfma_f32_16x16x32_bf16 v[24:27], v[66:69], v[54:57], v[24:27]
	v_mfma_f32_16x16x32_bf16 v[28:31], v[70:73], v[54:57], v[28:31]
	s_waitcnt vmcnt(3)
	s_barrier
	s_mov_b64 s[40:41], 0x480
	s_mov_b32 m0, s1
	v_lshl_add_u64 v[32:33], v[2:3], 0, s[40:41]
	global_load_lds_dwordx4 v[32:33], off
	v_lshl_add_u64 v[32:33], v[4:5], 0, s[40:41]
	s_mov_b32 m0, s6
	s_nop 0
	global_load_lds_dwordx4 v[32:33], off
	v_lshl_add_u64 v[32:33], v[6:7], 0, s[40:41]
	s_mov_b32 m0, s4
	s_nop 0
	global_load_lds_dwordx4 v[32:33], off
	ds_read_b128 v[32:35], v10 offset:0
	ds_read_b128 v[36:39], v0 offset:0
	ds_read_b128 v[42:45], v0 offset:2048
	ds_read_b128 v[46:49], v0 offset:4096
	ds_read_b128 v[50:53], v0 offset:6144
	ds_read_b128 v[54:57], v10 offset:1024
	ds_read_b128 v[58:61], v0 offset:1024
	ds_read_b128 v[62:65], v0 offset:3072
	ds_read_b128 v[66:69], v0 offset:5120
	ds_read_b128 v[70:73], v0 offset:7168
	s_waitcnt lgkmcnt(5)
	s_nop 0
	v_mfma_f32_16x16x32_bf16 v[14:17], v[36:39], v[32:35], v[14:17]
	v_mfma_f32_16x16x32_bf16 v[20:23], v[42:45], v[32:35], v[20:23]
	v_mfma_f32_16x16x32_bf16 v[24:27], v[46:49], v[32:35], v[24:27]
	v_mfma_f32_16x16x32_bf16 v[28:31], v[50:53], v[32:35], v[28:31]
	s_waitcnt lgkmcnt(0)
	v_mfma_f32_16x16x32_bf16 v[14:17], v[58:61], v[54:57], v[14:17]
	v_mfma_f32_16x16x32_bf16 v[20:23], v[62:65], v[54:57], v[20:23]
	v_mfma_f32_16x16x32_bf16 v[24:27], v[66:69], v[54:57], v[24:27]
	v_mfma_f32_16x16x32_bf16 v[28:31], v[70:73], v[54:57], v[28:31]
	s_waitcnt vmcnt(3)
	s_barrier
	s_mov_b64 s[40:41], 0x500
	s_mov_b32 m0, s7
	v_lshl_add_u64 v[32:33], v[2:3], 0, s[40:41]
	global_load_lds_dwordx4 v[32:33], off
	v_lshl_add_u64 v[32:33], v[4:5], 0, s[40:41]
	s_mov_b32 m0, s5
	s_nop 0
	global_load_lds_dwordx4 v[32:33], off
	v_lshl_add_u64 v[32:33], v[6:7], 0, s[40:41]
	s_mov_b32 m0, s9
	s_nop 0
	global_load_lds_dwordx4 v[32:33], off
	ds_read_b128 v[32:35], v12 offset:0
	ds_read_b128 v[36:39], v11 offset:0
	ds_read_b128 v[42:45], v11 offset:2048
	ds_read_b128 v[46:49], v11 offset:4096
	ds_read_b128 v[50:53], v11 offset:6144
	ds_read_b128 v[54:57], v12 offset:1024
	ds_read_b128 v[58:61], v11 offset:1024
	ds_read_b128 v[62:65], v11 offset:3072
	ds_read_b128 v[66:69], v11 offset:5120
	ds_read_b128 v[70:73], v11 offset:7168
	s_waitcnt lgkmcnt(5)
	s_nop 0
	v_mfma_f32_16x16x32_bf16 v[14:17], v[36:39], v[32:35], v[14:17]
	v_mfma_f32_16x16x32_bf16 v[20:23], v[42:45], v[32:35], v[20:23]
	v_mfma_f32_16x16x32_bf16 v[24:27], v[46:49], v[32:35], v[24:27]
	v_mfma_f32_16x16x32_bf16 v[28:31], v[50:53], v[32:35], v[28:31]
	s_waitcnt lgkmcnt(0)
	v_mfma_f32_16x16x32_bf16 v[14:17], v[58:61], v[54:57], v[14:17]
	v_mfma_f32_16x16x32_bf16 v[20:23], v[62:65], v[54:57], v[20:23]
	v_mfma_f32_16x16x32_bf16 v[24:27], v[66:69], v[54:57], v[24:27]
	v_mfma_f32_16x16x32_bf16 v[28:31], v[70:73], v[54:57], v[28:31]
	s_waitcnt vmcnt(3)
	s_barrier
	s_mov_b64 s[40:41], 0x580
	s_mov_b32 m0, s11
	v_lshl_add_u64 v[32:33], v[2:3], 0, s[40:41]
	global_load_lds_dwordx4 v[32:33], off
	v_lshl_add_u64 v[32:33], v[4:5], 0, s[40:41]
	s_mov_b32 m0, s10
	s_nop 0
	global_load_lds_dwordx4 v[32:33], off
	v_lshl_add_u64 v[32:33], v[6:7], 0, s[40:41]
	s_mov_b32 m0, s38
	s_nop 0
	global_load_lds_dwordx4 v[32:33], off
	ds_read_b128 v[32:35], v9 offset:0
	ds_read_b128 v[36:39], v8 offset:0
	ds_read_b128 v[42:45], v8 offset:2048
	ds_read_b128 v[46:49], v8 offset:4096
	ds_read_b128 v[50:53], v8 offset:6144
	ds_read_b128 v[54:57], v9 offset:1024
	ds_read_b128 v[58:61], v8 offset:1024
	ds_read_b128 v[62:65], v8 offset:3072
	ds_read_b128 v[66:69], v8 offset:5120
	ds_read_b128 v[70:73], v8 offset:7168
	s_waitcnt lgkmcnt(5)
	s_nop 0
	v_mfma_f32_16x16x32_bf16 v[14:17], v[36:39], v[32:35], v[14:17]
	v_mfma_f32_16x16x32_bf16 v[20:23], v[42:45], v[32:35], v[20:23]
	v_mfma_f32_16x16x32_bf16 v[24:27], v[46:49], v[32:35], v[24:27]
	v_mfma_f32_16x16x32_bf16 v[28:31], v[50:53], v[32:35], v[28:31]
	s_waitcnt lgkmcnt(0)
	v_mfma_f32_16x16x32_bf16 v[14:17], v[58:61], v[54:57], v[14:17]
	v_mfma_f32_16x16x32_bf16 v[20:23], v[62:65], v[54:57], v[20:23]
	v_mfma_f32_16x16x32_bf16 v[24:27], v[66:69], v[54:57], v[24:27]
	v_mfma_f32_16x16x32_bf16 v[28:31], v[70:73], v[54:57], v[28:31]
	s_waitcnt vmcnt(3)
	s_barrier
	s_mov_b64 s[40:41], 0x600
	s_mov_b32 m0, s1
	v_lshl_add_u64 v[32:33], v[2:3], 0, s[40:41]
	global_load_lds_dwordx4 v[32:33], off
	v_lshl_add_u64 v[32:33], v[4:5], 0, s[40:41]
	s_mov_b32 m0, s6
	s_nop 0
	global_load_lds_dwordx4 v[32:33], off
	v_lshl_add_u64 v[32:33], v[6:7], 0, s[40:41]
	s_mov_b32 m0, s4
	s_nop 0
	global_load_lds_dwordx4 v[32:33], off
	ds_read_b128 v[32:35], v10 offset:0
	ds_read_b128 v[36:39], v0 offset:0
	ds_read_b128 v[42:45], v0 offset:2048
	ds_read_b128 v[46:49], v0 offset:4096
	ds_read_b128 v[50:53], v0 offset:6144
	ds_read_b128 v[54:57], v10 offset:1024
	ds_read_b128 v[58:61], v0 offset:1024
	ds_read_b128 v[62:65], v0 offset:3072
	ds_read_b128 v[66:69], v0 offset:5120
	ds_read_b128 v[70:73], v0 offset:7168
	s_waitcnt lgkmcnt(5)
	s_nop 0
	v_mfma_f32_16x16x32_bf16 v[14:17], v[36:39], v[32:35], v[14:17]
	v_mfma_f32_16x16x32_bf16 v[20:23], v[42:45], v[32:35], v[20:23]
	v_mfma_f32_16x16x32_bf16 v[24:27], v[46:49], v[32:35], v[24:27]
	v_mfma_f32_16x16x32_bf16 v[28:31], v[50:53], v[32:35], v[28:31]
	s_waitcnt lgkmcnt(0)
	v_mfma_f32_16x16x32_bf16 v[14:17], v[58:61], v[54:57], v[14:17]
	v_mfma_f32_16x16x32_bf16 v[20:23], v[62:65], v[54:57], v[20:23]
	v_mfma_f32_16x16x32_bf16 v[24:27], v[66:69], v[54:57], v[24:27]
	v_mfma_f32_16x16x32_bf16 v[28:31], v[70:73], v[54:57], v[28:31]
	s_waitcnt vmcnt(3)
	s_barrier
	s_mov_b64 s[40:41], 0x680
	s_mov_b32 m0, s7
	v_lshl_add_u64 v[32:33], v[2:3], 0, s[40:41]
	global_load_lds_dwordx4 v[32:33], off
	v_lshl_add_u64 v[32:33], v[4:5], 0, s[40:41]
	s_mov_b32 m0, s5
	s_nop 0
	global_load_lds_dwordx4 v[32:33], off
	v_lshl_add_u64 v[32:33], v[6:7], 0, s[40:41]
	s_mov_b32 m0, s9
	s_nop 0
	global_load_lds_dwordx4 v[32:33], off
	ds_read_b128 v[32:35], v12 offset:0
	ds_read_b128 v[36:39], v11 offset:0
	ds_read_b128 v[42:45], v11 offset:2048
	ds_read_b128 v[46:49], v11 offset:4096
	ds_read_b128 v[50:53], v11 offset:6144
	ds_read_b128 v[54:57], v12 offset:1024
	ds_read_b128 v[58:61], v11 offset:1024
	ds_read_b128 v[62:65], v11 offset:3072
	ds_read_b128 v[66:69], v11 offset:5120
	ds_read_b128 v[70:73], v11 offset:7168
	s_waitcnt lgkmcnt(5)
	s_nop 0
	v_mfma_f32_16x16x32_bf16 v[14:17], v[36:39], v[32:35], v[14:17]
	v_mfma_f32_16x16x32_bf16 v[20:23], v[42:45], v[32:35], v[20:23]
	v_mfma_f32_16x16x32_bf16 v[24:27], v[46:49], v[32:35], v[24:27]
	v_mfma_f32_16x16x32_bf16 v[28:31], v[50:53], v[32:35], v[28:31]
	s_waitcnt lgkmcnt(0)
	v_mfma_f32_16x16x32_bf16 v[14:17], v[58:61], v[54:57], v[14:17]
	v_mfma_f32_16x16x32_bf16 v[20:23], v[62:65], v[54:57], v[20:23]
	v_mfma_f32_16x16x32_bf16 v[24:27], v[66:69], v[54:57], v[24:27]
	v_mfma_f32_16x16x32_bf16 v[28:31], v[70:73], v[54:57], v[28:31]
	s_waitcnt vmcnt(3)
	s_barrier
	s_mov_b64 s[40:41], 0x700
	s_mov_b32 m0, s11
	v_lshl_add_u64 v[32:33], v[2:3], 0, s[40:41]
	global_load_lds_dwordx4 v[32:33], off
	v_lshl_add_u64 v[32:33], v[4:5], 0, s[40:41]
	s_mov_b32 m0, s10
	s_nop 0
	global_load_lds_dwordx4 v[32:33], off
	v_lshl_add_u64 v[32:33], v[6:7], 0, s[40:41]
	s_mov_b32 m0, s38
	s_nop 0
	global_load_lds_dwordx4 v[32:33], off
	ds_read_b128 v[32:35], v9 offset:0
	ds_read_b128 v[36:39], v8 offset:0
	ds_read_b128 v[42:45], v8 offset:2048
	ds_read_b128 v[46:49], v8 offset:4096
	ds_read_b128 v[50:53], v8 offset:6144
	ds_read_b128 v[54:57], v9 offset:1024
	ds_read_b128 v[58:61], v8 offset:1024
	ds_read_b128 v[62:65], v8 offset:3072
	ds_read_b128 v[66:69], v8 offset:5120
	ds_read_b128 v[70:73], v8 offset:7168
	s_waitcnt lgkmcnt(5)
	s_nop 0
	v_mfma_f32_16x16x32_bf16 v[14:17], v[36:39], v[32:35], v[14:17]
	v_mfma_f32_16x16x32_bf16 v[20:23], v[42:45], v[32:35], v[20:23]
	v_mfma_f32_16x16x32_bf16 v[24:27], v[46:49], v[32:35], v[24:27]
	v_mfma_f32_16x16x32_bf16 v[28:31], v[50:53], v[32:35], v[28:31]
	s_waitcnt lgkmcnt(0)
	v_mfma_f32_16x16x32_bf16 v[14:17], v[58:61], v[54:57], v[14:17]
	v_mfma_f32_16x16x32_bf16 v[20:23], v[62:65], v[54:57], v[20:23]
	v_mfma_f32_16x16x32_bf16 v[24:27], v[66:69], v[54:57], v[24:27]
	v_mfma_f32_16x16x32_bf16 v[28:31], v[70:73], v[54:57], v[28:31]
	s_waitcnt vmcnt(3)
	s_barrier
	s_mov_b64 s[10:11], 0x780
	s_mov_b32 m0, s1
	v_lshl_add_u64 v[2:3], v[2:3], 0, s[10:11]
	global_load_lds_dwordx4 v[2:3], off
	v_lshl_add_u64 v[2:3], v[4:5], 0, s[10:11]
	s_mov_b32 m0, s6
	s_nop 0
	global_load_lds_dwordx4 v[2:3], off
	v_lshl_add_u64 v[2:3], v[6:7], 0, s[10:11]
	s_mov_b32 m0, s4
	s_nop 0
	global_load_lds_dwordx4 v[2:3], off
	ds_read_b128 v[2:5], v10 offset:0
	ds_read_b128 v[32:35], v0 offset:0
	ds_read_b128 v[36:39], v0 offset:2048
	ds_read_b128 v[42:45], v0 offset:4096
	ds_read_b128 v[46:49], v0 offset:6144
	ds_read_b128 v[50:53], v10 offset:1024
	ds_read_b128 v[54:57], v0 offset:1024
	ds_read_b128 v[58:61], v0 offset:3072
	ds_read_b128 v[62:65], v0 offset:5120
	ds_read_b128 v[66:69], v0 offset:7168
	s_waitcnt lgkmcnt(5)
	s_nop 0
	v_mfma_f32_16x16x32_bf16 v[14:17], v[32:35], v[2:5], v[14:17]
	v_mfma_f32_16x16x32_bf16 v[20:23], v[36:39], v[2:5], v[20:23]
	v_mfma_f32_16x16x32_bf16 v[24:27], v[42:45], v[2:5], v[24:27]
	v_mfma_f32_16x16x32_bf16 v[2:5], v[46:49], v[2:5], v[28:31]
	s_waitcnt lgkmcnt(0)
	v_mfma_f32_16x16x32_bf16 v[14:17], v[54:57], v[50:53], v[14:17]
	v_mfma_f32_16x16x32_bf16 v[2:5], v[66:69], v[50:53], v[2:5]
	v_mfma_f32_16x16x32_bf16 v[20:23], v[58:61], v[50:53], v[20:23]
	v_mfma_f32_16x16x32_bf16 v[24:27], v[62:65], v[50:53], v[24:27]
	s_waitcnt vmcnt(3)
	s_barrier
	ds_read_b128 v[28:31], v12 offset:0
	ds_read_b128 v[32:35], v11 offset:0
	ds_read_b128 v[36:39], v11 offset:2048
	ds_read_b128 v[42:45], v11 offset:4096
	ds_read_b128 v[46:49], v11 offset:6144
	ds_read_b128 v[50:53], v12 offset:1024
	ds_read_b128 v[54:57], v11 offset:1024
	ds_read_b128 v[58:61], v11 offset:3072
	ds_read_b128 v[62:65], v11 offset:5120
	ds_read_b128 v[10:13], v11 offset:7168
	s_waitcnt lgkmcnt(5)
	s_nop 0
	v_mfma_f32_16x16x32_bf16 v[14:17], v[32:35], v[28:31], v[14:17]
	v_mfma_f32_16x16x32_bf16 v[2:5], v[46:49], v[28:31], v[2:5]
	v_mfma_f32_16x16x32_bf16 v[20:23], v[36:39], v[28:31], v[20:23]
	v_mfma_f32_16x16x32_bf16 v[24:27], v[42:45], v[28:31], v[24:27]
	s_waitcnt lgkmcnt(0)
	v_mfma_f32_16x16x32_bf16 v[14:17], v[54:57], v[50:53], v[14:17]
	v_mfma_f32_16x16x32_bf16 v[2:5], v[10:13], v[50:53], v[2:5]
	v_mfma_f32_16x16x32_bf16 v[20:23], v[58:61], v[50:53], v[20:23]
	v_mfma_f32_16x16x32_bf16 v[24:27], v[62:65], v[50:53], v[24:27]
	s_waitcnt vmcnt(0)
	v_and_b32_e32 v0, 15, v18
	v_bfe_u32 v41, v18, 4, 2
	s_barrier
	ds_read_b128 v[10:13], v9 offset:0
	ds_read_b128 v[28:31], v8 offset:0
	ds_read_b128 v[32:35], v8 offset:2048
	ds_read_b128 v[36:39], v8 offset:4096
	ds_read_b128 v[42:45], v8 offset:6144
	ds_read_b128 v[46:49], v9 offset:1024
	ds_read_b128 v[50:53], v8 offset:1024
	ds_read_b128 v[54:57], v8 offset:3072
	ds_read_b128 v[58:61], v8 offset:5120
	ds_read_b128 v[62:65], v8 offset:7168
	s_waitcnt lgkmcnt(5)
	s_nop 0
	v_mfma_f32_16x16x32_bf16 v[6:9], v[28:31], v[10:13], v[14:17]
	v_mfma_f32_16x16x32_bf16 v[2:5], v[42:45], v[10:13], v[2:5]
	v_mfma_f32_16x16x32_bf16 v[20:23], v[32:35], v[10:13], v[20:23]
	v_mfma_f32_16x16x32_bf16 v[24:27], v[36:39], v[10:13], v[24:27]
	s_waitcnt lgkmcnt(0)
	v_mfma_f32_16x16x32_bf16 v[14:17], v[50:53], v[46:49], v[6:9]
	v_mfma_f32_16x16x32_bf16 v[10:13], v[54:57], v[46:49], v[20:23]
	v_mfma_f32_16x16x32_bf16 v[6:9], v[58:61], v[46:49], v[24:27]
	v_mfma_f32_16x16x32_bf16 v[2:5], v[62:65], v[46:49], v[2:5]
	v_ashrrev_i32_e32 v19, 3, v18
	v_and_b32_e32 v42, -16, v19
	s_cmp_gt_i32 s19, 7
	s_mov_b64 s[4:5], -1
	v_readlane_b32 s1, v215, 34
	s_cbranch_scc0 .LBB0_369
	s_cmp_gt_u32 s19, 15
	s_cbranch_scc0 .LBB0_364
	s_cmpk_gt_i32 s0, 0xfff
	s_cselect_b64 s[4:5], -1, 0
	s_addk_i32 s8, 0xf000
	s_lshr_b32 s1, s8, 10
	s_cmpk_lt_i32 s0, 0x1000
	s_cselect_b64 s[6:7], -1, 0
	s_and_b64 s[8:9], s[6:7], exec
	s_movk_i32 s8, 0x3c0
	s_cselect_b32 s8, 0xc0, s8
	s_and_b32 s8, s8, s0
	v_add_u32_e32 v18, s8, v42
	s_cmp_gt_u32 s19, 31
	s_mov_b64 s[8:9], -1
	s_cbranch_scc0 .LBB0_349
	s_cmp_gt_u32 s19, 39
	s_cbranch_scc0 .LBB0_342
	v_add_u32_e32 v20, s0, v42
	v_mul_f32_e32 v24, 0xbfb8aa3b, v14
	v_mul_f32_e32 v25, 0xbfb8aa3b, v15
	v_mul_f32_e32 v26, 0xbfb8aa3b, v16
	v_mul_f32_e32 v27, 0xbfb8aa3b, v17
	v_or_b32_e32 v20, v20, v0
	v_exp_f32_e32 v24, v24
	v_exp_f32_e32 v25, v25
	v_exp_f32_e32 v26, v26
	v_exp_f32_e32 v27, v27
	v_ashrrev_i32_e32 v21, 31, v20
	v_lshlrev_b64 v[20:21], 12, v[20:21]
	v_lshl_add_u64 v[20:21], s[48:49], 0, v[20:21]
	v_lshl_add_u64 v[20:21], s[2:3], 1, v[20:21]
	v_lshlrev_b32_e32 v22, 7, v40
	v_mov_b32_e32 v23, v1
	v_add_f32_e32 v24, 1.0, v24
	v_add_f32_e32 v25, 1.0, v25
	v_add_f32_e32 v26, 1.0, v26
	v_add_f32_e32 v27, 1.0, v27
	v_lshl_add_u64 v[20:21], v[20:21], 0, v[22:23]
	v_lshlrev_b32_e32 v22, 3, v41
	v_rcp_f32_e32 v24, v24
	v_rcp_f32_e32 v25, v25
	v_rcp_f32_e32 v26, v26
	v_rcp_f32_e32 v27, v27
	v_lshl_add_u64 v[22:23], v[20:21], 0, v[22:23]
	s_mov_b64 s[8:9], 0xa15d800
	v_lshl_add_u64 v[20:21], v[22:23], 0, s[8:9]
	s_mov_b32 s8, 0xa15d000
	v_add_co_u32_e32 v22, vcc, s8, v22
	v_cvt_pk_bf16_f32 v24, v24, v25
	v_cvt_pk_bf16_f32 v25, v26, v27
	v_addc_co_u32_e32 v23, vcc, 0, v23, vcc
	global_store_dwordx2 v[22:23], v[24:25], off offset:2048
	v_mul_f32_e32 v22, 0xbfb8aa3b, v10
	v_mul_f32_e32 v23, 0xbfb8aa3b, v11
	v_mul_f32_e32 v24, 0xbfb8aa3b, v12
	v_mul_f32_e32 v25, 0xbfb8aa3b, v13
	v_exp_f32_e32 v22, v22
	v_exp_f32_e32 v23, v23
	v_exp_f32_e32 v24, v24
	v_exp_f32_e32 v25, v25
	v_add_f32_e32 v22, 1.0, v22
	v_add_f32_e32 v23, 1.0, v23
	v_add_f32_e32 v24, 1.0, v24
	v_add_f32_e32 v25, 1.0, v25
	v_rcp_f32_e32 v22, v22
	v_rcp_f32_e32 v23, v23
	v_rcp_f32_e32 v24, v24
	v_rcp_f32_e32 v25, v25
	s_mov_b64 s[8:9], 0
	v_cvt_pk_bf16_f32 v22, v22, v23
	v_cvt_pk_bf16_f32 v23, v24, v25
	global_store_dwordx2 v[20:21], v[22:23], off offset:32
	v_mul_f32_e32 v22, 0xbfb8aa3b, v6
	v_mul_f32_e32 v23, 0xbfb8aa3b, v7
	v_mul_f32_e32 v24, 0xbfb8aa3b, v8
	v_mul_f32_e32 v25, 0xbfb8aa3b, v9
	v_exp_f32_e32 v22, v22
	v_exp_f32_e32 v23, v23
	v_exp_f32_e32 v24, v24
	v_exp_f32_e32 v25, v25
	v_add_f32_e32 v22, 1.0, v22
	v_add_f32_e32 v23, 1.0, v23
	v_add_f32_e32 v24, 1.0, v24
	v_add_f32_e32 v25, 1.0, v25
	v_rcp_f32_e32 v22, v22
	v_rcp_f32_e32 v23, v23
	v_rcp_f32_e32 v24, v24
	v_rcp_f32_e32 v25, v25
	v_cvt_pk_bf16_f32 v22, v22, v23
	v_cvt_pk_bf16_f32 v23, v24, v25
	global_store_dwordx2 v[20:21], v[22:23], off offset:64
	v_mul_f32_e32 v22, 0xbfb8aa3b, v2
	v_mul_f32_e32 v23, 0xbfb8aa3b, v3
	v_mul_f32_e32 v24, 0xbfb8aa3b, v4
	v_mul_f32_e32 v25, 0xbfb8aa3b, v5
	v_exp_f32_e32 v22, v22
	v_exp_f32_e32 v23, v23
	v_exp_f32_e32 v24, v24
	v_exp_f32_e32 v25, v25
	v_add_f32_e32 v22, 1.0, v22
	v_add_f32_e32 v23, 1.0, v23
	v_add_f32_e32 v24, 1.0, v24
	v_add_f32_e32 v25, 1.0, v25
	v_rcp_f32_e32 v22, v22
	v_rcp_f32_e32 v23, v23
	v_rcp_f32_e32 v24, v24
	v_rcp_f32_e32 v25, v25
	v_cvt_pk_bf16_f32 v22, v22, v23
	v_cvt_pk_bf16_f32 v23, v24, v25
	global_store_dwordx2 v[20:21], v[22:23], off offset:96
